# NSA selected-branch loop: V fragments preloaded at block top (no LDS waits between PV MFMAs); transposes rows 0 and 14 batched too
# speedup vs baseline: 1.0152x; 1.0152x over previous
; DI void transpose_tile(const float* __restrict__ src, int sld, int k0, int n0, int kind, u16* __restrict__ dst, int dld,
;                        char* ldsraw) {
;     ...
; #pragma unroll
;     for (int i = 0; i < 16; ++i) {
;       const int kk = kq * 16 + i;
;       t[kk * 65 + nn] = (sc >= 0) ? src[(size_t)(k0 + kk) * sld + sc] : 0.f;
;     }
.LBB0_68:
	s_or_b64 exec, exec, s[0:1]
	v_readlane_b32 s0, v251, 63
	v_ashrrev_i32_e32 v5, 2, v4
	v_readlane_b32 s1, v252, 0
	s_and_b32 s2, s6, 0x3c0
	v_and_b32_e32 v6, -16, v5
	v_cmp_lt_i32_e32 vcc, -1, v0
	v_lshl_add_u64 v[2:3], v[0:1], 2, s[0:1]
	v_mov_b32_e32 v8, 0
	v_mov_b32_e32 v9, 0
	v_mov_b32_e32 v228, 0
	v_mov_b32_e32 v229, 0
	v_mov_b32_e32 v230, 0
	v_mov_b32_e32 v231, 0
	v_mov_b32_e32 v232, 0
	v_mov_b32_e32 v233, 0
	v_mov_b32_e32 v234, 0
	v_mov_b32_e32 v235, 0
	v_mov_b32_e32 v236, 0
	v_mov_b32_e32 v237, 0
	v_mov_b32_e32 v238, 0
	v_mov_b32_e32 v239, 0
	v_mov_b32_e32 v240, 0
	v_mov_b32_e32 v241, 0
	v_mov_b32_e32 v242, 0
	s_and_saveexec_b64 s[0:1], vcc
	s_cbranch_execz .Lbt_1
	v_add_u32_e32 v246, s2, v6
	v_mad_i64_i32 v[246:247], s[10:11], v246, s58, v[2:3]
	global_load_dword v228, v[246:247], off
	v_add3_u32 v246, s2, v6, 1
	v_mad_i64_i32 v[246:247], s[10:11], v246, s58, v[2:3]
	global_load_dword v229, v[246:247], off
	v_add3_u32 v246, s2, v6, 2
	v_mad_i64_i32 v[246:247], s[10:11], v246, s58, v[2:3]
	global_load_dword v230, v[246:247], off
	v_add3_u32 v246, s2, v6, 3
	v_mad_i64_i32 v[246:247], s[10:11], v246, s58, v[2:3]
	global_load_dword v231, v[246:247], off
	v_add3_u32 v246, s2, v6, 4
	v_mad_i64_i32 v[246:247], s[10:11], v246, s58, v[2:3]
	global_load_dword v232, v[246:247], off
	v_add3_u32 v246, s2, v6, 5
	v_mad_i64_i32 v[246:247], s[10:11], v246, s58, v[2:3]
	global_load_dword v233, v[246:247], off
	v_add3_u32 v246, s2, v6, 6
	v_mad_i64_i32 v[246:247], s[10:11], v246, s58, v[2:3]
	global_load_dword v234, v[246:247], off
	v_add3_u32 v246, s2, v6, 7
	v_mad_i64_i32 v[246:247], s[10:11], v246, s58, v[2:3]
	global_load_dword v235, v[246:247], off
	v_add3_u32 v246, s2, v6, 8
	v_mad_i64_i32 v[246:247], s[10:11], v246, s58, v[2:3]
	global_load_dword v236, v[246:247], off
	v_add3_u32 v246, s2, v6, 9
	v_mad_i64_i32 v[246:247], s[10:11], v246, s58, v[2:3]
	global_load_dword v237, v[246:247], off
	v_add3_u32 v246, s2, v6, 10
	v_mad_i64_i32 v[246:247], s[10:11], v246, s58, v[2:3]
	global_load_dword v238, v[246:247], off
	v_add3_u32 v246, s2, v6, 11
	v_mad_i64_i32 v[246:247], s[10:11], v246, s58, v[2:3]
	global_load_dword v239, v[246:247], off
	v_add3_u32 v246, s2, v6, 12
	v_mad_i64_i32 v[246:247], s[10:11], v246, s58, v[2:3]
	global_load_dword v240, v[246:247], off
	v_add3_u32 v246, s2, v6, 13
	v_mad_i64_i32 v[246:247], s[10:11], v246, s58, v[2:3]
	global_load_dword v241, v[246:247], off
	v_add3_u32 v246, s2, v6, 14
	v_mad_i64_i32 v[246:247], s[10:11], v246, s58, v[2:3]
	global_load_dword v242, v[246:247], off
.Lbt_1:
	s_or_b64 exec, exec, s[0:1]
	v_and_b32_e32 v0, 63, v4
	v_lshlrev_b32_e32 v0, 2, v0
	v_mul_lo_u32 v7, v6, s57
	v_add_u32_e32 v7, v0, v7
	v_or_b32_e32 v6, 15, v5
	s_waitcnt vmcnt(14)
	ds_write_b32 v7, v228
	s_waitcnt vmcnt(13)
	ds_write_b32 v7, v229 offset:260
	s_waitcnt vmcnt(12)
	ds_write_b32 v7, v230 offset:520
	s_waitcnt vmcnt(11)
	ds_write_b32 v7, v231 offset:780
	s_waitcnt vmcnt(10)
	ds_write_b32 v7, v232 offset:1040
	s_waitcnt vmcnt(9)
	ds_write_b32 v7, v233 offset:1300
	s_waitcnt vmcnt(8)
	ds_write_b32 v7, v234 offset:1560
	s_waitcnt vmcnt(7)
	ds_write_b32 v7, v235 offset:1820
	s_waitcnt vmcnt(6)
	ds_write_b32 v7, v236 offset:2080
	s_waitcnt vmcnt(5)
	ds_write_b32 v7, v237 offset:2340
	s_waitcnt vmcnt(4)
	ds_write_b32 v7, v238 offset:2600
	s_waitcnt vmcnt(3)
	ds_write_b32 v7, v239 offset:2860
	s_waitcnt vmcnt(2)
	ds_write_b32 v7, v240 offset:3120
	s_waitcnt vmcnt(1)
	ds_write_b32 v7, v241 offset:3380
	s_waitcnt vmcnt(0)
	ds_write_b32 v7, v242 offset:3640
	v_mov_b32_e32 v8, 0
	v_mov_b32_e32 v9, 0
	s_and_saveexec_b64 s[0:1], vcc
	s_cbranch_execz .LBB0_37
	v_add_u32_e32 v7, s2, v6
	v_mad_i64_i32 v[2:3], s[10:11], v7, s58, v[2:3]
	global_load_dword v8, v[2:3], off
	s_branch .LBB0_37

; DI void transpose_tile(const float* __restrict__ src, int sld, int k0, int n0, int kind, u16* __restrict__ dst, int dld,
;                        char* ldsraw) {
;     ...
; #pragma unroll
;     for (int i = 0; i < 16; ++i) {
;       const int kk = kq * 16 + i;
;       t[kk * 65 + nn] = (sc >= 0) ? src[(size_t)(k0 + kk) * sld + sc] : 0.f;
;     }
.LBB0_143:
	s_or_b64 exec, exec, s[0:1]
	v_readlane_b32 s36, v251, 2
	s_lshl_b32 s0, s5, 6
	v_ashrrev_i32_e32 v5, 2, v4
	v_readlane_b32 s40, v251, 6
	v_readlane_b32 s41, v251, 7
	s_and_b32 s2, s0, 0x3c0
	v_and_b32_e32 v6, -16, v5
	v_cmp_lt_i32_e32 vcc, -1, v0
	v_lshl_add_u64 v[2:3], v[0:1], 2, s[40:41]
	v_mov_b32_e32 v8, 0
	v_mov_b32_e32 v9, 0
	v_readlane_b32 s37, v251, 3
	v_readlane_b32 s38, v251, 4
	v_readlane_b32 s39, v251, 5
	v_readlane_b32 s42, v251, 8
	v_readlane_b32 s43, v251, 9
	v_readlane_b32 s44, v251, 10
	v_readlane_b32 s45, v251, 11
	v_readlane_b32 s46, v251, 12
	v_readlane_b32 s47, v251, 13
	v_readlane_b32 s48, v251, 14
	v_readlane_b32 s49, v251, 15
	v_readlane_b32 s50, v251, 16
	v_readlane_b32 s51, v251, 17
	v_mov_b32_e32 v228, 0
	v_mov_b32_e32 v229, 0
	v_mov_b32_e32 v230, 0
	v_mov_b32_e32 v231, 0
	v_mov_b32_e32 v232, 0
	v_mov_b32_e32 v233, 0
	v_mov_b32_e32 v234, 0
	v_mov_b32_e32 v235, 0
	v_mov_b32_e32 v236, 0
	v_mov_b32_e32 v237, 0
	v_mov_b32_e32 v238, 0
	v_mov_b32_e32 v239, 0
	v_mov_b32_e32 v240, 0
	v_mov_b32_e32 v241, 0
	s_and_saveexec_b64 s[0:1], vcc
	s_cbranch_execz .Lbt_2
	v_add_u32_e32 v246, s2, v6
	v_mad_i64_i32 v[246:247], s[8:9], v246, s58, v[2:3]
	global_load_dword v228, v[246:247], off
	v_add3_u32 v246, s2, v6, 1
	v_mad_i64_i32 v[246:247], s[8:9], v246, s58, v[2:3]
	global_load_dword v229, v[246:247], off
	v_add3_u32 v246, s2, v6, 2
	v_mad_i64_i32 v[246:247], s[8:9], v246, s58, v[2:3]
	global_load_dword v230, v[246:247], off
	v_add3_u32 v246, s2, v6, 3
	v_mad_i64_i32 v[246:247], s[8:9], v246, s58, v[2:3]
	global_load_dword v231, v[246:247], off
	v_add3_u32 v246, s2, v6, 4
	v_mad_i64_i32 v[246:247], s[8:9], v246, s58, v[2:3]
	global_load_dword v232, v[246:247], off
	v_add3_u32 v246, s2, v6, 5
	v_mad_i64_i32 v[246:247], s[8:9], v246, s58, v[2:3]
	global_load_dword v233, v[246:247], off
	v_add3_u32 v246, s2, v6, 6
	v_mad_i64_i32 v[246:247], s[8:9], v246, s58, v[2:3]
	global_load_dword v234, v[246:247], off
	v_add3_u32 v246, s2, v6, 7
	v_mad_i64_i32 v[246:247], s[8:9], v246, s58, v[2:3]
	global_load_dword v235, v[246:247], off
	v_add3_u32 v246, s2, v6, 8
	v_mad_i64_i32 v[246:247], s[8:9], v246, s58, v[2:3]
	global_load_dword v236, v[246:247], off
	v_add3_u32 v246, s2, v6, 9
	v_mad_i64_i32 v[246:247], s[8:9], v246, s58, v[2:3]
	global_load_dword v237, v[246:247], off
	v_add3_u32 v246, s2, v6, 10
	v_mad_i64_i32 v[246:247], s[8:9], v246, s58, v[2:3]
	global_load_dword v238, v[246:247], off
	v_add3_u32 v246, s2, v6, 11
	v_mad_i64_i32 v[246:247], s[8:9], v246, s58, v[2:3]
	global_load_dword v239, v[246:247], off
	v_add3_u32 v246, s2, v6, 12
	v_mad_i64_i32 v[246:247], s[8:9], v246, s58, v[2:3]
	global_load_dword v240, v[246:247], off
	v_add3_u32 v246, s2, v6, 13
	v_mad_i64_i32 v[246:247], s[8:9], v246, s58, v[2:3]
	global_load_dword v241, v[246:247], off
.Lbt_2:
	s_or_b64 exec, exec, s[0:1]
	v_and_b32_e32 v0, 63, v4
	v_lshlrev_b32_e32 v0, 2, v0
	v_mul_lo_u32 v7, v6, s57
	v_add_u32_e32 v7, v0, v7
	s_waitcnt vmcnt(13)
	ds_write_b32 v7, v228
	s_waitcnt vmcnt(12)
	ds_write_b32 v7, v229 offset:260
	s_waitcnt vmcnt(11)
	ds_write_b32 v7, v230 offset:520
	s_waitcnt vmcnt(10)
	ds_write_b32 v7, v231 offset:780
	s_waitcnt vmcnt(9)
	ds_write_b32 v7, v232 offset:1040
	s_waitcnt vmcnt(8)
	ds_write_b32 v7, v233 offset:1300
	s_waitcnt vmcnt(7)
	ds_write_b32 v7, v234 offset:1560
	s_waitcnt vmcnt(6)
	ds_write_b32 v7, v235 offset:1820
	s_waitcnt vmcnt(5)
	ds_write_b32 v7, v236 offset:2080
	s_waitcnt vmcnt(4)
	ds_write_b32 v7, v237 offset:2340
	s_waitcnt vmcnt(3)
	ds_write_b32 v7, v238 offset:2600
	s_waitcnt vmcnt(2)
	ds_write_b32 v7, v239 offset:2860
	s_waitcnt vmcnt(1)
	ds_write_b32 v7, v240 offset:3120
	s_waitcnt vmcnt(0)
	ds_write_b32 v7, v241 offset:3380
	v_mov_b32_e32 v8, 0
	v_mov_b32_e32 v9, 0
	v_mov_b32_e32 v8, 0
	v_mov_b32_e32 v9, 0
	s_and_saveexec_b64 s[0:1], vcc
	s_cbranch_execz .LBB0_173
	v_add3_u32 v6, s2, v6, 14
	v_mad_i64_i32 v[10:11], s[8:9], v6, s58, v[2:3]
	global_load_dword v9, v[10:11], off

; DI void transpose_tile(const float* __restrict__ src, int sld, int k0, int n0, int kind, u16* __restrict__ dst, int dld,
;                        char* ldsraw) {
;     ...
; #pragma unroll
;     for (int i = 0; i < 16; ++i) {
;       const int kk = kq * 16 + i;
;       t[kk * 65 + nn] = (sc >= 0) ? src[(size_t)(k0 + kk) * sld + sc] : 0.f;
;     }
.LBB0_555:
	s_or_b64 exec, exec, s[0:1]
	s_lshl_b32 s0, s4, 6
	s_and_b32 s2, s0, 0x3c0
	v_readlane_b32 s0, v251, 63
	v_ashrrev_i32_e32 v5, 2, v4
	v_readlane_b32 s1, v252, 0
	v_and_b32_e32 v6, -16, v5
	v_cmp_lt_i32_e32 vcc, -1, v0
	v_lshl_add_u64 v[2:3], v[0:1], 2, s[0:1]
	v_mov_b32_e32 v8, 0
	v_mov_b32_e32 v9, 0
	v_mov_b32_e32 v228, 0
	v_mov_b32_e32 v229, 0
	v_mov_b32_e32 v230, 0
	v_mov_b32_e32 v231, 0
	v_mov_b32_e32 v232, 0
	v_mov_b32_e32 v233, 0
	v_mov_b32_e32 v234, 0
	v_mov_b32_e32 v235, 0
	v_mov_b32_e32 v236, 0
	v_mov_b32_e32 v237, 0
	v_mov_b32_e32 v238, 0
	v_mov_b32_e32 v239, 0
	v_mov_b32_e32 v240, 0
	v_mov_b32_e32 v241, 0
	v_mov_b32_e32 v242, 0
	s_and_saveexec_b64 s[0:1], vcc
	s_cbranch_execz .Lbt_3
	v_add_u32_e32 v246, s2, v6
	v_mad_i64_i32 v[246:247], s[6:7], v246, s58, v[2:3]
	global_load_dword v228, v[246:247], off
	v_add3_u32 v246, s2, v6, 1
	v_mad_i64_i32 v[246:247], s[6:7], v246, s58, v[2:3]
	global_load_dword v229, v[246:247], off
	v_add3_u32 v246, s2, v6, 2
	v_mad_i64_i32 v[246:247], s[6:7], v246, s58, v[2:3]
	global_load_dword v230, v[246:247], off
	v_add3_u32 v246, s2, v6, 3
	v_mad_i64_i32 v[246:247], s[6:7], v246, s58, v[2:3]
	global_load_dword v231, v[246:247], off
	v_add3_u32 v246, s2, v6, 4
	v_mad_i64_i32 v[246:247], s[6:7], v246, s58, v[2:3]
	global_load_dword v232, v[246:247], off
	v_add3_u32 v246, s2, v6, 5
	v_mad_i64_i32 v[246:247], s[6:7], v246, s58, v[2:3]
	global_load_dword v233, v[246:247], off
	v_add3_u32 v246, s2, v6, 6
	v_mad_i64_i32 v[246:247], s[6:7], v246, s58, v[2:3]
	global_load_dword v234, v[246:247], off
	v_add3_u32 v246, s2, v6, 7
	v_mad_i64_i32 v[246:247], s[6:7], v246, s58, v[2:3]
	global_load_dword v235, v[246:247], off
	v_add3_u32 v246, s2, v6, 8
	v_mad_i64_i32 v[246:247], s[6:7], v246, s58, v[2:3]
	global_load_dword v236, v[246:247], off
	v_add3_u32 v246, s2, v6, 9
	v_mad_i64_i32 v[246:247], s[6:7], v246, s58, v[2:3]
	global_load_dword v237, v[246:247], off
	v_add3_u32 v246, s2, v6, 10
	v_mad_i64_i32 v[246:247], s[6:7], v246, s58, v[2:3]
	global_load_dword v238, v[246:247], off
	v_add3_u32 v246, s2, v6, 11
	v_mad_i64_i32 v[246:247], s[6:7], v246, s58, v[2:3]
	global_load_dword v239, v[246:247], off
	v_add3_u32 v246, s2, v6, 12
	v_mad_i64_i32 v[246:247], s[6:7], v246, s58, v[2:3]
	global_load_dword v240, v[246:247], off
	v_add3_u32 v246, s2, v6, 13
	v_mad_i64_i32 v[246:247], s[6:7], v246, s58, v[2:3]
	global_load_dword v241, v[246:247], off
	v_add3_u32 v246, s2, v6, 14
	v_mad_i64_i32 v[246:247], s[6:7], v246, s58, v[2:3]
	global_load_dword v242, v[246:247], off
.Lbt_3:
	s_or_b64 exec, exec, s[0:1]
	v_and_b32_e32 v0, 63, v4
	v_lshlrev_b32_e32 v0, 2, v0
	v_mul_lo_u32 v7, v6, s57
	v_add_u32_e32 v7, v0, v7
	v_or_b32_e32 v6, 15, v5
	s_waitcnt vmcnt(14)
	ds_write_b32 v7, v228
	s_waitcnt vmcnt(13)
	ds_write_b32 v7, v229 offset:260
	s_waitcnt vmcnt(12)
	ds_write_b32 v7, v230 offset:520
	s_waitcnt vmcnt(11)
	ds_write_b32 v7, v231 offset:780
	s_waitcnt vmcnt(10)
	ds_write_b32 v7, v232 offset:1040
	s_waitcnt vmcnt(9)
	ds_write_b32 v7, v233 offset:1300
	s_waitcnt vmcnt(8)
	ds_write_b32 v7, v234 offset:1560
	s_waitcnt vmcnt(7)
	ds_write_b32 v7, v235 offset:1820
	s_waitcnt vmcnt(6)
	ds_write_b32 v7, v236 offset:2080
	s_waitcnt vmcnt(5)
	ds_write_b32 v7, v237 offset:2340
	s_waitcnt vmcnt(4)
	ds_write_b32 v7, v238 offset:2600
	s_waitcnt vmcnt(3)
	ds_write_b32 v7, v239 offset:2860
	s_waitcnt vmcnt(2)
	ds_write_b32 v7, v240 offset:3120
	s_waitcnt vmcnt(1)
	ds_write_b32 v7, v241 offset:3380
	s_waitcnt vmcnt(0)
	ds_write_b32 v7, v242 offset:3640
	v_mov_b32_e32 v8, 0
	v_mov_b32_e32 v9, 0
	s_and_saveexec_b64 s[0:1], vcc
	s_cbranch_execz .LBB0_506
	v_add_u32_e32 v7, s2, v6
	v_mad_i64_i32 v[2:3], s[6:7], v7, s58, v[2:3]
	global_load_dword v8, v[2:3], off
	s_branch .LBB0_506

; #define MFMA(a, b, c) __builtin_amdgcn_mfma_f32_32x32x16_f16(__builtin_bit_cast(h16x8, (a)), __builtin_bit_cast(h16x8, (b)), (c), 0, 0, 0)
; DI unsigned pk2(float a, float b) { f2_t v = {a, b}; bf2_t r = __builtin_convertvector(v, bf2_t); return __builtin_bit_cast(unsigned, r); }
; template <int MODE> ...
;     ...
;             float ps = 0.f;
; #pragma unroll
;             for (int i = 0; i < 16; ++i) {
;               sv[i] = __builtin_amdgcn_exp2f(sv[i] - mc);
;               ps += sv[i];
;             }
;             l[nb] += ps;
; #pragma unroll
;             for (int s2 = 0; s2 < 2; ++s2) {
;               const unsigned u0 = pk2(sv[8 * s2], sv[8 * s2 + 1]), u1 = pk2(sv[8 * s2 + 2], sv[8 * s2 + 3]);
;               const unsigned u2 = pk2(sv[8 * s2 + 4], sv[8 * s2 + 5]), u3 = pk2(sv[8 * s2 + 6], sv[8 * s2 + 7]);
;               const uint4 uu = make_uint4(u0, u1, u2, u3);
;               pk[nb][s2] = __builtin_bit_cast(bf16x8, uu);
;             }
;           }
;         }
;         if (MODE != M_CMP2) {
; #pragma unroll
;           for (int s2 = 0; s2 < 2; ++s2) {
; #pragma unroll
;             for (int db = 0; db < 2; ++db) {
;               const u16* vp = Vt + (kb * 32 + 16 * s2 + 4 * h + q4) * LDK + db * 32 + 16 * blk + 4 * p4;
;               const s16x4 lo = __builtin_amdgcn_ds_read_tr16_b64_v4i16((__attribute__((address_space(3))) s16x4*)(vp));
;               const s16x4 hi = __builtin_amdgcn_ds_read_tr16_b64_v4i16((__attribute__((address_space(3))) s16x4*)(vp + 8 * LDK));
;               const bf16x8 a = __builtin_shufflevector(lo, hi, 0, 1, 2, 3, 4, 5, 6, 7);
;               O[db][0] = MFMA(a, pk[0][s2], O[db][0]);
;               O[db][1] = MFMA(a, pk[1][s2], O[db][1]);
;             }
;           }
.LBB0_729:
	v_or_b32_e32 v244, s17, v189
	v_mad_u32_u24 v244, v244, s76, v206
	ds_read_b64_tr_b16 v[228:229], v244 offset:18432
	ds_read_b64_tr_b16 v[230:231], v244 offset:19584
	ds_read_b64_tr_b16 v[232:233], v244 offset:18496
	ds_read_b64_tr_b16 v[234:235], v244 offset:19648
	ds_read_b64_tr_b16 v[236:237], v244 offset:20736
	ds_read_b64_tr_b16 v[238:239], v244 offset:21888
	ds_read_b64_tr_b16 v[240:241], v244 offset:20800
	ds_read_b64_tr_b16 v[242:243], v244 offset:21952
	v_add_f32_e32 v2, 0, v208
	v_add_f32_e32 v2, v210, v2
	v_add_f32_e32 v2, v212, v2
	v_add_f32_e32 v2, v213, v2
	v_add_f32_e32 v2, v214, v2
	v_add_f32_e32 v2, v164, v2
	v_add_f32_e32 v2, v166, v2
	v_add_f32_e32 v2, v167, v2
	v_add_f32_e32 v2, v165, v2
	v_add_f32_e32 v2, v215, v2
	v_add_f32_e32 v2, v216, v2
	v_add_f32_e32 v2, v217, v2
	v_add_f32_e32 v2, v6, v2
	v_add_f32_e32 v2, v7, v2
	v_cvt_pk_f16_f32 v4, v6, v7
	v_sub_f32_e32 v6, v80, v205
	v_add_f32_e32 v2, v8, v2
	v_cvt_pk_f16_f32 v5, v8, v9
	v_exp_f32_e32 v6, v6
	v_sub_f32_e32 v8, v81, v205
	v_add_f32_e32 v2, v9, v2
	v_exp_f32_e32 v8, v8
	v_sub_f32_e32 v9, v82, v205
	v_exp_f32_e32 v9, v9
	v_sub_f32_e32 v80, v83, v205
	v_exp_f32_e32 v81, v80
	v_sub_f32_e32 v80, v84, v205
	v_add_f32_e32 v7, 0, v6
	v_exp_f32_e32 v82, v80
	v_sub_f32_e32 v80, v85, v205
	v_add_f32_e32 v7, v8, v7
	v_exp_f32_e32 v83, v80
	v_sub_f32_e32 v80, v86, v205
	v_add_f32_e32 v7, v9, v7
	v_exp_f32_e32 v84, v80
	v_sub_f32_e32 v80, v87, v205
	v_add_f32_e32 v7, v81, v7
	v_exp_f32_e32 v85, v80
	v_sub_f32_e32 v80, v88, v205
	v_add_f32_e32 v7, v82, v7
	v_exp_f32_e32 v86, v80
	v_sub_f32_e32 v80, v89, v205
	v_add_f32_e32 v7, v83, v7
	v_exp_f32_e32 v87, v80
	v_sub_f32_e32 v80, v90, v205
	v_add_f32_e32 v7, v84, v7
	v_exp_f32_e32 v88, v80
	v_sub_f32_e32 v80, v91, v205
	v_add_f32_e32 v7, v85, v7
	v_exp_f32_e32 v89, v80
	v_sub_f32_e32 v80, v92, v205
	v_add_f32_e32 v7, v86, v7
	v_exp_f32_e32 v90, v80
	v_sub_f32_e32 v80, v93, v205
	v_add_f32_e32 v7, v87, v7
	v_exp_f32_e32 v91, v80
	v_sub_f32_e32 v80, v94, v205
	v_add_f32_e32 v7, v88, v7
	v_exp_f32_e32 v92, v80
	v_sub_f32_e32 v80, v95, v205
	v_add_f32_e32 v7, v89, v7
	v_exp_f32_e32 v93, v80
	v_add_f32_e32 v7, v90, v7
	v_add_f32_e32 v7, v91, v7
	v_add_f32_e32 v7, v92, v7
	v_add_f32_e32 v7, v93, v7
	v_cvt_pk_f16_f32 v82, v82, v83
	v_cvt_pk_f16_f32 v83, v84, v85
	v_or_b32_e32 v84, s17, v189
	v_add_f32_e32 v180, v180, v7
	v_cvt_pk_f16_f32 v7, v88, v89
	v_mad_u32_u24 v88, v84, s76, v206
	v_cvt_pk_f16_f32 v80, v6, v8
	v_cvt_pk_f16_f32 v6, v86, v87
	v_cvt_pk_f16_f32 v10, v208, v210
	v_cvt_pk_f16_f32 v11, v212, v213
	v_cvt_pk_f16_f32 v12, v214, v164
	v_cvt_pk_f16_f32 v13, v166, v167
	v_cvt_pk_f16_f32 v81, v9, v81
	v_add_f32_e32 v14, v14, v2
	s_waitcnt lgkmcnt(0)
	v_mfma_f32_32x32x16_f16 v[64:79], v[228:231], v[10:13], v[64:79]
	v_cvt_pk_f16_f32 v2, v165, v215
	v_cvt_pk_f16_f32 v3, v216, v217
	v_cvt_pk_f16_f32 v8, v90, v91
	v_cvt_pk_f16_f32 v9, v92, v93
	v_mfma_f32_32x32x16_f16 v[32:47], v[228:231], v[80:83], v[32:47]
	s_waitcnt lgkmcnt(0)
	v_mfma_f32_32x32x16_f16 v[48:63], v[232:235], v[10:13], v[48:63]
	v_mfma_f32_32x32x16_f16 v[16:31], v[232:235], v[80:83], v[16:31]
	v_mov_b32_e32 v80, v14
	s_waitcnt lgkmcnt(0)
	v_mfma_f32_32x32x16_f16 v[64:79], v[236:239], v[2:5], v[64:79]
	v_mfma_f32_32x32x16_f16 v[32:47], v[236:239], v[6:9], v[32:47]
	s_waitcnt lgkmcnt(0)
	v_mfma_f32_32x32x16_f16 v[48:63], v[240:243], v[2:5], v[48:63]
	v_mfma_f32_32x32x16_f16 v[16:31], v[240:243], v[6:9], v[16:31]
